# v56 + fp8 GEMM K-loops: stray mid-segment lgkmcnt(0) hoisted out of the P13 loop, B1 fragment read deferral (lgkmcnt(4) at barrier, lgkmcnt(0) at first B1 consumer) in P12/P13
# baseline (speedup 1.0000x reference)
.LBB0_2480:
	ds_read_b128 v[18:21], v182
	ds_read_b128 v[22:25], v182 offset:1024
	ds_read_b128 v[26:29], v182 offset:2048
	ds_read_b128 v[30:33], v182 offset:3072
	s_add_u32 s26, s24, 0xfc000
	s_addc_u32 s27, s25, 0
	s_cmp_eq_u32 s48, 28
	s_cselect_b32 s30, s17, s26
	s_cselect_b32 s31, s5, s27
	s_cselect_b32 s28, s23, s46
	s_cselect_b32 s29, s15, s47
	s_add_u32 s26, s30, 0x100000
	s_addc_u32 s27, s31, 0
	s_add_i32 m0, s34, 0xc000
	ds_read_b128 v[186:189], v184
	ds_read_b128 v[190:193], v184 offset:1024
	ds_read_b128 v[220:223], v184 offset:2048
	ds_read_b128 v[224:227], v184 offset:3072
	ds_read_b128 v[228:231], v184 offset:4096
	ds_read_b128 v[232:235], v184 offset:5120
	ds_read_b128 v[236:239], v184 offset:6144
	ds_read_b128 v[240:243], v184 offset:7168
	global_load_lds_dwordx4 v172, s[24:25]
	s_add_i32 m0, s34, 0xe000
	s_nop 0
	global_load_lds_dwordx4 v174, s[24:25]
	ds_read_b128 v[2:5], v183
	ds_read_b128 v[6:9], v183 offset:1024
	ds_read_b128 v[10:13], v183 offset:2048
	ds_read_b128 v[14:17], v183 offset:3072
	s_waitcnt vmcnt(8)
	s_waitcnt lgkmcnt(4)
	s_setprio 1
	s_barrier
	v_mfma_f32_16x16x128_f8f6f4 v[158:161], v[18:25], v[186:193], v[158:161]
	v_mfma_f32_16x16x128_f8f6f4 v[154:157], v[26:33], v[186:193], v[154:157]
	v_mfma_f32_16x16x128_f8f6f4 v[142:145], v[18:25], v[220:227], v[142:145]
	v_mfma_f32_16x16x128_f8f6f4 v[138:141], v[26:33], v[220:227], v[138:141]
	v_mfma_f32_16x16x128_f8f6f4 v[126:129], v[18:25], v[228:235], v[126:129]
	v_mfma_f32_16x16x128_f8f6f4 v[122:125], v[26:33], v[228:235], v[122:125]
	v_mfma_f32_16x16x128_f8f6f4 v[110:113], v[18:25], v[236:243], v[110:113]
	v_mfma_f32_16x16x128_f8f6f4 v[106:109], v[26:33], v[236:243], v[106:109]
	s_setprio 0
	s_setprio 1
	s_waitcnt lgkmcnt(0)
	v_mfma_f32_16x16x128_f8f6f4 v[150:153], v[2:9], v[186:193], v[150:153]
	v_mfma_f32_16x16x128_f8f6f4 v[146:149], v[10:17], v[186:193], v[146:149]
	v_mfma_f32_16x16x128_f8f6f4 v[134:137], v[2:9], v[220:227], v[134:137]
	v_mfma_f32_16x16x128_f8f6f4 v[130:133], v[10:17], v[220:227], v[130:133]
	v_mfma_f32_16x16x128_f8f6f4 v[118:121], v[2:9], v[228:235], v[118:121]
	v_mfma_f32_16x16x128_f8f6f4 v[114:117], v[10:17], v[228:235], v[114:117]
	v_mfma_f32_16x16x128_f8f6f4 v[102:105], v[2:9], v[236:243], v[102:105]
	v_mfma_f32_16x16x128_f8f6f4 v[98:101], v[10:17], v[236:243], v[98:101]
	s_barrier
	s_setprio 0
	s_add_i32 s49, s42, s0
	s_mov_b32 m0, s49
	ds_read_b128 v[186:189], v184 offset:16384
	ds_read_b128 v[190:193], v184 offset:17408
	ds_read_b128 v[220:223], v184 offset:18432
	ds_read_b128 v[224:227], v184 offset:19456
	ds_read_b128 v[228:231], v184 offset:20480
	ds_read_b128 v[232:235], v184 offset:21504
	ds_read_b128 v[236:239], v184 offset:22528
	ds_read_b128 v[240:243], v184 offset:23552
	global_load_lds_dwordx4 v166, s[28:29]
	s_add_i32 m0, s49, 0x2000
	s_add_u32 s50, s28, 0x4000
	s_addc_u32 s51, s29, 0
	s_add_i32 s49, s43, s0
	global_load_lds_dwordx4 v162, s[28:29]
	s_mov_b32 m0, s49
	s_nop 0
	global_load_lds_dwordx4 v166, s[50:51]
	s_add_i32 m0, s49, 0x2000
	s_nop 0
	global_load_lds_dwordx4 v162, s[50:51]
	s_mov_b32 m0, s34
	s_nop 0
	global_load_lds_dwordx4 v168, s[30:31]
	s_mov_b32 m0, s35
	s_nop 0
	global_load_lds_dwordx4 v164, s[30:31]
	s_waitcnt vmcnt(8)
	s_waitcnt lgkmcnt(0)
	s_setprio 1
	s_barrier
	v_mfma_f32_16x16x128_f8f6f4 v[94:97], v[18:25], v[186:193], v[94:97]
	v_mfma_f32_16x16x128_f8f6f4 v[90:93], v[26:33], v[186:193], v[90:93]
	v_mfma_f32_16x16x128_f8f6f4 v[78:81], v[18:25], v[220:227], v[78:81]
	v_mfma_f32_16x16x128_f8f6f4 v[74:77], v[26:33], v[220:227], v[74:77]
	v_mfma_f32_16x16x128_f8f6f4 v[62:65], v[18:25], v[228:235], v[62:65]
	v_mfma_f32_16x16x128_f8f6f4 v[58:61], v[26:33], v[228:235], v[58:61]
	v_mfma_f32_16x16x128_f8f6f4 v[46:49], v[18:25], v[236:243], v[46:49]
	v_mfma_f32_16x16x128_f8f6f4 v[42:45], v[26:33], v[236:243], v[42:45]
	s_setprio 0
	s_setprio 1
	v_mfma_f32_16x16x128_f8f6f4 v[86:89], v[2:9], v[186:193], v[86:89]
	v_mfma_f32_16x16x128_f8f6f4 v[82:85], v[10:17], v[186:193], v[82:85]
	v_mfma_f32_16x16x128_f8f6f4 v[70:73], v[2:9], v[220:227], v[70:73]
	v_mfma_f32_16x16x128_f8f6f4 v[66:69], v[10:17], v[220:227], v[66:69]
	v_mfma_f32_16x16x128_f8f6f4 v[54:57], v[2:9], v[228:235], v[54:57]
	v_mfma_f32_16x16x128_f8f6f4 v[50:53], v[10:17], v[228:235], v[50:53]
	v_mfma_f32_16x16x128_f8f6f4 v[38:41], v[2:9], v[236:243], v[38:41]
	v_mfma_f32_16x16x128_f8f6f4 v[34:37], v[10:17], v[236:243], v[34:37]
	s_barrier
	s_setprio 0
	s_add_i32 s49, 0, 0x18000
	s_add_i32 s50, 0, 0x1c000
	v_add_u32_e32 v14, s49, v181
	v_add_u32_e32 v30, s50, v181
	ds_read_b128 v[2:5], v14
	ds_read_b128 v[6:9], v14 offset:1024
	ds_read_b128 v[10:13], v14 offset:2048
	ds_read_b128 v[14:17], v14 offset:3072
	s_add_u32 s30, s30, 0x4000
	s_addc_u32 s31, s31, 0
	s_mov_b32 m0, s36
	ds_read_b128 v[186:189], v184 offset:32768
	ds_read_b128 v[190:193], v184 offset:33792
	ds_read_b128 v[220:223], v184 offset:34816
	ds_read_b128 v[224:227], v184 offset:35840
	ds_read_b128 v[228:231], v184 offset:36864
	ds_read_b128 v[232:235], v184 offset:37888
	ds_read_b128 v[236:239], v184 offset:38912
	ds_read_b128 v[240:243], v184 offset:39936
	global_load_lds_dwordx4 v168, s[30:31]
	s_mov_b32 m0, s37
	s_nop 0
	global_load_lds_dwordx4 v164, s[30:31]
	ds_read_b128 v[18:21], v30
	ds_read_b128 v[22:25], v30 offset:1024
	ds_read_b128 v[26:29], v30 offset:2048
	ds_read_b128 v[30:33], v30 offset:3072
	s_waitcnt vmcnt(8)
	s_waitcnt lgkmcnt(4)
	s_setprio 1
	s_barrier
	v_mfma_f32_16x16x128_f8f6f4 v[158:161], v[2:9], v[186:193], v[158:161]
	v_mfma_f32_16x16x128_f8f6f4 v[154:157], v[10:17], v[186:193], v[154:157]
	v_mfma_f32_16x16x128_f8f6f4 v[142:145], v[2:9], v[220:227], v[142:145]
	v_mfma_f32_16x16x128_f8f6f4 v[138:141], v[10:17], v[220:227], v[138:141]
	v_mfma_f32_16x16x128_f8f6f4 v[126:129], v[2:9], v[228:235], v[126:129]
	v_mfma_f32_16x16x128_f8f6f4 v[122:125], v[10:17], v[228:235], v[122:125]
	v_mfma_f32_16x16x128_f8f6f4 v[110:113], v[2:9], v[236:243], v[110:113]
	v_mfma_f32_16x16x128_f8f6f4 v[106:109], v[10:17], v[236:243], v[106:109]
	s_setprio 0
	s_setprio 1
	s_waitcnt lgkmcnt(0)
	v_mfma_f32_16x16x128_f8f6f4 v[150:153], v[18:25], v[186:193], v[150:153]
	v_mfma_f32_16x16x128_f8f6f4 v[146:149], v[26:33], v[186:193], v[146:149]
	v_mfma_f32_16x16x128_f8f6f4 v[134:137], v[18:25], v[220:227], v[134:137]
	v_mfma_f32_16x16x128_f8f6f4 v[130:133], v[26:33], v[220:227], v[130:133]
	v_mfma_f32_16x16x128_f8f6f4 v[118:121], v[18:25], v[228:235], v[118:121]
	v_mfma_f32_16x16x128_f8f6f4 v[114:117], v[26:33], v[228:235], v[114:117]
	v_mfma_f32_16x16x128_f8f6f4 v[102:105], v[18:25], v[236:243], v[102:105]
	v_mfma_f32_16x16x128_f8f6f4 v[98:101], v[26:33], v[236:243], v[98:101]
	s_barrier
	s_setprio 0
	s_add_u32 s30, s28, 0x380000
	s_addc_u32 s31, s29, 0
	s_add_i32 s49, s49, s0
	s_mov_b32 m0, s49
	ds_read_b128 v[186:189], v184 offset:49152
	ds_read_b128 v[190:193], v184 offset:50176
	ds_read_b128 v[220:223], v184 offset:51200
	ds_read_b128 v[224:227], v184 offset:52224
	ds_read_b128 v[228:231], v184 offset:53248
	ds_read_b128 v[232:235], v184 offset:54272
	ds_read_b128 v[236:239], v184 offset:55296
	ds_read_b128 v[240:243], v184 offset:56320
	global_load_lds_dwordx4 v166, s[30:31]
	s_add_i32 m0, s49, 0x2000
	s_add_u32 s28, s28, 0x384000
	s_addc_u32 s29, s29, 0
	global_load_lds_dwordx4 v162, s[30:31]
	s_add_i32 s30, s50, s0
	s_mov_b32 m0, s30
	s_nop 0
	global_load_lds_dwordx4 v166, s[28:29]
	s_add_i32 m0, s30, 0x2000
	s_nop 0
	global_load_lds_dwordx4 v162, s[28:29]
	s_mov_b32 m0, s40
	s_nop 0
	global_load_lds_dwordx4 v168, s[26:27]
	s_mov_b32 m0, s41
	s_nop 0
	global_load_lds_dwordx4 v164, s[26:27]
	s_waitcnt vmcnt(8)
	s_waitcnt lgkmcnt(0)
	s_setprio 1
	s_barrier
	v_mfma_f32_16x16x128_f8f6f4 v[94:97], v[2:9], v[186:193], v[94:97]
	v_mfma_f32_16x16x128_f8f6f4 v[90:93], v[10:17], v[186:193], v[90:93]
	v_mfma_f32_16x16x128_f8f6f4 v[78:81], v[2:9], v[220:227], v[78:81]
	v_mfma_f32_16x16x128_f8f6f4 v[74:77], v[10:17], v[220:227], v[74:77]
	v_mfma_f32_16x16x128_f8f6f4 v[62:65], v[2:9], v[228:235], v[62:65]
	v_mfma_f32_16x16x128_f8f6f4 v[58:61], v[10:17], v[228:235], v[58:61]
	v_mfma_f32_16x16x128_f8f6f4 v[46:49], v[2:9], v[236:243], v[46:49]
	v_mfma_f32_16x16x128_f8f6f4 v[42:45], v[10:17], v[236:243], v[42:45]
	s_setprio 0
	s_setprio 1
	v_mfma_f32_16x16x128_f8f6f4 v[86:89], v[18:25], v[186:193], v[86:89]
	v_mfma_f32_16x16x128_f8f6f4 v[82:85], v[26:33], v[186:193], v[82:85]
	v_mfma_f32_16x16x128_f8f6f4 v[70:73], v[18:25], v[220:227], v[70:73]
	v_mfma_f32_16x16x128_f8f6f4 v[66:69], v[26:33], v[220:227], v[66:69]
	v_mfma_f32_16x16x128_f8f6f4 v[54:57], v[18:25], v[228:235], v[54:57]
	v_mfma_f32_16x16x128_f8f6f4 v[50:53], v[26:33], v[228:235], v[50:53]
	v_mfma_f32_16x16x128_f8f6f4 v[38:41], v[18:25], v[236:243], v[38:41]
	v_mfma_f32_16x16x128_f8f6f4 v[34:37], v[26:33], v[236:243], v[34:37]
	s_barrier
	s_setprio 0
	s_add_i32 s48, s48, 2
	s_add_u32 s46, s46, 0x700000
	s_addc_u32 s47, s47, 0
	s_add_u32 s24, s24, 0x200000
	s_addc_u32 s25, s25, 0
	s_cmp_gt_u32 s48, 29
	s_cbranch_scc0 .LBB0_2480
	s_and_b64 vcc, exec, s[8:9]
	s_cbranch_vccz .LBB0_2483
	s_barrier

.LBB0_2713:
	s_ashr_i32 s17, s16, 31
	s_lshl_b64 s[18:19], s[16:17], 15
	v_readlane_b32 s20, v245, 14
	v_readlane_b32 s21, v245, 15
	s_add_u32 s18, s20, s18
	s_addc_u32 s19, s21, s19
	s_and_b64 s[20:21], s[8:9], exec
	s_cselect_b32 s5, s19, s25
	s_cselect_b32 s17, s18, s24
	s_ashr_i32 s15, s14, 31
	s_lshl_b64 s[20:21], s[14:15], 15
	s_add_u32 s20, s88, s20
	s_addc_u32 s21, s89, s21
	s_and_b64 s[26:27], s[8:9], exec
	s_cselect_b32 s15, s21, s23
	s_cselect_b32 s41, s20, s22
	s_add_u32 s42, s22, 0x100000
	s_addc_u32 s43, s23, 0
	s_add_u32 s22, s24, 0x104000
	v_mov_b32_e32 v34, 0
	s_addc_u32 s23, s25, 0
	s_mov_b32 s44, -2
	v_mov_b32_e32 v35, 0
	v_mov_b64_e32 v[36:37], 0
	v_mov_b64_e32 v[38:39], 0
	v_mov_b64_e32 v[40:41], 0
	v_mov_b64_e32 v[42:43], 0
	v_mov_b64_e32 v[44:45], 0
	v_mov_b64_e32 v[46:47], 0
	v_mov_b64_e32 v[48:49], 0
	v_mov_b64_e32 v[50:51], 0
	v_mov_b64_e32 v[52:53], 0
	v_mov_b64_e32 v[54:55], 0
	v_mov_b64_e32 v[56:57], 0
	v_mov_b64_e32 v[58:59], 0
	v_mov_b64_e32 v[60:61], 0
	v_mov_b64_e32 v[62:63], 0
	v_mov_b64_e32 v[64:65], 0
	v_mov_b64_e32 v[66:67], 0
	v_mov_b64_e32 v[68:69], 0
	v_mov_b64_e32 v[70:71], 0
	v_mov_b64_e32 v[72:73], 0
	v_mov_b64_e32 v[74:75], 0
	v_mov_b64_e32 v[76:77], 0
	v_mov_b64_e32 v[78:79], 0
	v_mov_b64_e32 v[80:81], 0
	v_mov_b64_e32 v[82:83], 0
	v_mov_b64_e32 v[84:85], 0
	v_mov_b64_e32 v[86:87], 0
	v_mov_b64_e32 v[88:89], 0
	v_mov_b64_e32 v[90:91], 0
	v_mov_b64_e32 v[92:93], 0
	v_mov_b64_e32 v[94:95], 0
	v_mov_b64_e32 v[96:97], 0
	v_mov_b64_e32 v[98:99], 0
	v_mov_b64_e32 v[100:101], 0
	v_mov_b64_e32 v[102:103], 0
	v_mov_b64_e32 v[104:105], 0
	v_mov_b64_e32 v[106:107], 0
	v_mov_b64_e32 v[108:109], 0
	v_mov_b64_e32 v[110:111], 0
	v_mov_b64_e32 v[112:113], 0
	v_mov_b64_e32 v[114:115], 0
	v_mov_b64_e32 v[116:117], 0
	v_mov_b64_e32 v[118:119], 0
	v_mov_b64_e32 v[120:121], 0
	v_mov_b64_e32 v[122:123], 0
	v_mov_b64_e32 v[124:125], 0
	v_mov_b64_e32 v[126:127], 0
	v_mov_b64_e32 v[128:129], 0
	v_mov_b64_e32 v[130:131], 0
	v_mov_b64_e32 v[132:133], 0
	v_mov_b64_e32 v[134:135], 0
	v_mov_b64_e32 v[136:137], 0
	v_mov_b64_e32 v[138:139], 0
	v_mov_b64_e32 v[140:141], 0
	v_mov_b64_e32 v[142:143], 0
	v_mov_b64_e32 v[144:145], 0
	v_mov_b64_e32 v[146:147], 0
	v_mov_b64_e32 v[148:149], 0
	v_mov_b64_e32 v[150:151], 0
	v_mov_b64_e32 v[152:153], 0
	v_mov_b64_e32 v[154:155], 0
	v_mov_b64_e32 v[156:157], 0
	v_mov_b64_e32 v[158:159], 0
	v_mov_b64_e32 v[160:161], 0
	s_waitcnt lgkmcnt(0)
.LBB0_2714:
	ds_read_b128 v[18:21], v180
	ds_read_b128 v[22:25], v180 offset:1024
	ds_read_b128 v[26:29], v180 offset:2048
	ds_read_b128 v[30:33], v180 offset:3072
	s_add_u32 s24, s22, 0xfc000
	s_addc_u32 s25, s23, 0
	s_cmpk_eq_i32 s44, 0x6c
	s_cselect_b32 s28, s17, s24
	s_cselect_b32 s29, s5, s25
	s_cselect_b32 s26, s41, s42
	s_cselect_b32 s27, s15, s43
	s_add_u32 s24, s28, 0x100000
	s_addc_u32 s25, s29, 0
	s_add_i32 m0, s1, 0xc000
	ds_read_b128 v[184:187], v182
	ds_read_b128 v[188:191], v182 offset:1024
	ds_read_b128 v[192:195], v182 offset:2048
	ds_read_b128 v[196:199], v182 offset:3072
	ds_read_b128 v[220:223], v182 offset:4096
	ds_read_b128 v[224:227], v182 offset:5120
	ds_read_b128 v[228:231], v182 offset:6144
	ds_read_b128 v[232:235], v182 offset:7168
	global_load_lds_dwordx4 v170, s[22:23]
	s_add_i32 m0, s1, 0xe000
	s_nop 0
	global_load_lds_dwordx4 v172, s[22:23]
	ds_read_b128 v[2:5], v181
	ds_read_b128 v[6:9], v181 offset:1024
	ds_read_b128 v[10:13], v181 offset:2048
	ds_read_b128 v[14:17], v181 offset:3072
	s_waitcnt vmcnt(8)
	s_waitcnt lgkmcnt(4)
	s_setprio 1
	s_barrier
	v_mfma_f32_16x16x128_f8f6f4 v[158:161], v[18:25], v[184:191], v[158:161]
	v_mfma_f32_16x16x128_f8f6f4 v[154:157], v[26:33], v[184:191], v[154:157]
	v_mfma_f32_16x16x128_f8f6f4 v[142:145], v[18:25], v[192:199], v[142:145]
	v_mfma_f32_16x16x128_f8f6f4 v[138:141], v[26:33], v[192:199], v[138:141]
	v_mfma_f32_16x16x128_f8f6f4 v[126:129], v[18:25], v[220:227], v[126:129]
	v_mfma_f32_16x16x128_f8f6f4 v[122:125], v[26:33], v[220:227], v[122:125]
	v_mfma_f32_16x16x128_f8f6f4 v[110:113], v[18:25], v[228:235], v[110:113]
	v_mfma_f32_16x16x128_f8f6f4 v[106:109], v[26:33], v[228:235], v[106:109]
	s_setprio 0
	s_setprio 1
	s_waitcnt lgkmcnt(0)
	v_mfma_f32_16x16x128_f8f6f4 v[150:153], v[2:9], v[184:191], v[150:153]
	v_mfma_f32_16x16x128_f8f6f4 v[146:149], v[10:17], v[184:191], v[146:149]
	v_mfma_f32_16x16x128_f8f6f4 v[134:137], v[2:9], v[192:199], v[134:137]
	v_mfma_f32_16x16x128_f8f6f4 v[130:133], v[10:17], v[192:199], v[130:133]
	v_mfma_f32_16x16x128_f8f6f4 v[118:121], v[2:9], v[220:227], v[118:121]
	v_mfma_f32_16x16x128_f8f6f4 v[114:117], v[10:17], v[220:227], v[114:117]
	v_mfma_f32_16x16x128_f8f6f4 v[102:105], v[2:9], v[228:235], v[102:105]
	v_mfma_f32_16x16x128_f8f6f4 v[98:101], v[10:17], v[228:235], v[98:101]
	s_barrier
	s_setprio 0
	s_add_i32 s45, s38, s0
	s_mov_b32 m0, s45
	ds_read_b128 v[184:187], v182 offset:16384
	ds_read_b128 v[188:191], v182 offset:17408
	ds_read_b128 v[192:195], v182 offset:18432
	ds_read_b128 v[196:199], v182 offset:19456
	ds_read_b128 v[220:223], v182 offset:20480
	ds_read_b128 v[224:227], v182 offset:21504
	ds_read_b128 v[228:231], v182 offset:22528
	ds_read_b128 v[232:235], v182 offset:23552
	global_load_lds_dwordx4 v164, s[26:27]
	s_add_i32 m0, s45, 0x2000
	s_add_u32 s46, s26, 0x4000
	s_addc_u32 s47, s27, 0
	s_add_i32 s45, s39, s0
	global_load_lds_dwordx4 v168, s[26:27]
	s_mov_b32 m0, s45
	s_nop 0
	global_load_lds_dwordx4 v164, s[46:47]
	s_add_i32 m0, s45, 0x2000
	s_nop 0
	global_load_lds_dwordx4 v168, s[46:47]
	s_mov_b32 m0, s1
	s_nop 0
	global_load_lds_dwordx4 v162, s[28:29]
	s_mov_b32 m0, s13
	s_nop 0
	global_load_lds_dwordx4 v166, s[28:29]
	s_waitcnt vmcnt(8)
	s_waitcnt lgkmcnt(0)
	s_setprio 1
	s_barrier
	v_mfma_f32_16x16x128_f8f6f4 v[94:97], v[18:25], v[184:191], v[94:97]
	v_mfma_f32_16x16x128_f8f6f4 v[90:93], v[26:33], v[184:191], v[90:93]
	v_mfma_f32_16x16x128_f8f6f4 v[78:81], v[18:25], v[192:199], v[78:81]
	v_mfma_f32_16x16x128_f8f6f4 v[74:77], v[26:33], v[192:199], v[74:77]
	v_mfma_f32_16x16x128_f8f6f4 v[62:65], v[18:25], v[220:227], v[62:65]
	v_mfma_f32_16x16x128_f8f6f4 v[58:61], v[26:33], v[220:227], v[58:61]
	v_mfma_f32_16x16x128_f8f6f4 v[46:49], v[18:25], v[228:235], v[46:49]
	v_mfma_f32_16x16x128_f8f6f4 v[42:45], v[26:33], v[228:235], v[42:45]
	s_setprio 0
	s_setprio 1
	v_mfma_f32_16x16x128_f8f6f4 v[86:89], v[2:9], v[184:191], v[86:89]
	v_mfma_f32_16x16x128_f8f6f4 v[82:85], v[10:17], v[184:191], v[82:85]
	v_mfma_f32_16x16x128_f8f6f4 v[70:73], v[2:9], v[192:199], v[70:73]
	v_mfma_f32_16x16x128_f8f6f4 v[66:69], v[10:17], v[192:199], v[66:69]
	v_mfma_f32_16x16x128_f8f6f4 v[54:57], v[2:9], v[220:227], v[54:57]
	v_mfma_f32_16x16x128_f8f6f4 v[50:53], v[10:17], v[220:227], v[50:53]
	v_mfma_f32_16x16x128_f8f6f4 v[38:41], v[2:9], v[228:235], v[38:41]
	v_mfma_f32_16x16x128_f8f6f4 v[34:37], v[10:17], v[228:235], v[34:37]
	s_barrier
	s_setprio 0
	s_add_i32 s45, 0, 0x18000
	s_add_i32 s46, 0, 0x1c000
	v_add_u32_e32 v14, s45, v179
	v_add_u32_e32 v30, s46, v179
	ds_read_b128 v[2:5], v14
	ds_read_b128 v[6:9], v14 offset:1024
	ds_read_b128 v[10:13], v14 offset:2048
	ds_read_b128 v[14:17], v14 offset:3072
	s_add_u32 s28, s28, 0x4000
	s_addc_u32 s29, s29, 0
	s_mov_b32 m0, s30
	ds_read_b128 v[184:187], v182 offset:32768
	ds_read_b128 v[188:191], v182 offset:33792
	ds_read_b128 v[192:195], v182 offset:34816
	ds_read_b128 v[196:199], v182 offset:35840
	ds_read_b128 v[220:223], v182 offset:36864
	ds_read_b128 v[224:227], v182 offset:37888
	ds_read_b128 v[228:231], v182 offset:38912
	ds_read_b128 v[232:235], v182 offset:39936
	global_load_lds_dwordx4 v162, s[28:29]
	s_mov_b32 m0, s31
	s_nop 0
	global_load_lds_dwordx4 v166, s[28:29]
	ds_read_b128 v[18:21], v30
	ds_read_b128 v[22:25], v30 offset:1024
	ds_read_b128 v[26:29], v30 offset:2048
	ds_read_b128 v[30:33], v30 offset:3072
	s_waitcnt vmcnt(8)
	s_waitcnt lgkmcnt(4)
	s_setprio 1
	s_barrier
	v_mfma_f32_16x16x128_f8f6f4 v[158:161], v[2:9], v[184:191], v[158:161]
	v_mfma_f32_16x16x128_f8f6f4 v[154:157], v[10:17], v[184:191], v[154:157]
	v_mfma_f32_16x16x128_f8f6f4 v[142:145], v[2:9], v[192:199], v[142:145]
	v_mfma_f32_16x16x128_f8f6f4 v[138:141], v[10:17], v[192:199], v[138:141]
	v_mfma_f32_16x16x128_f8f6f4 v[126:129], v[2:9], v[220:227], v[126:129]
	v_mfma_f32_16x16x128_f8f6f4 v[122:125], v[10:17], v[220:227], v[122:125]
	v_mfma_f32_16x16x128_f8f6f4 v[110:113], v[2:9], v[228:235], v[110:113]
	v_mfma_f32_16x16x128_f8f6f4 v[106:109], v[10:17], v[228:235], v[106:109]
	s_setprio 0
	s_setprio 1
	s_waitcnt lgkmcnt(0)
	v_mfma_f32_16x16x128_f8f6f4 v[150:153], v[18:25], v[184:191], v[150:153]
	v_mfma_f32_16x16x128_f8f6f4 v[146:149], v[26:33], v[184:191], v[146:149]
	v_mfma_f32_16x16x128_f8f6f4 v[134:137], v[18:25], v[192:199], v[134:137]
	v_mfma_f32_16x16x128_f8f6f4 v[130:133], v[26:33], v[192:199], v[130:133]
	v_mfma_f32_16x16x128_f8f6f4 v[118:121], v[18:25], v[220:227], v[118:121]
	v_mfma_f32_16x16x128_f8f6f4 v[114:117], v[26:33], v[220:227], v[114:117]
	v_mfma_f32_16x16x128_f8f6f4 v[102:105], v[18:25], v[228:235], v[102:105]
	v_mfma_f32_16x16x128_f8f6f4 v[98:101], v[26:33], v[228:235], v[98:101]
	s_barrier
	s_setprio 0
	s_add_u32 s28, s26, 0x80000
	s_addc_u32 s29, s27, 0
	s_add_i32 s45, s45, s0
	s_mov_b32 m0, s45
	ds_read_b128 v[184:187], v182 offset:49152
	ds_read_b128 v[188:191], v182 offset:50176
	ds_read_b128 v[192:195], v182 offset:51200
	ds_read_b128 v[196:199], v182 offset:52224
	ds_read_b128 v[220:223], v182 offset:53248
	ds_read_b128 v[224:227], v182 offset:54272
	ds_read_b128 v[228:231], v182 offset:55296
	ds_read_b128 v[232:235], v182 offset:56320
	global_load_lds_dwordx4 v164, s[28:29]
	s_add_i32 m0, s45, 0x2000
	s_add_u32 s26, s26, 0x84000
	s_addc_u32 s27, s27, 0
	global_load_lds_dwordx4 v168, s[28:29]
	s_add_i32 s28, s46, s0
	s_mov_b32 m0, s28
	s_nop 0
	global_load_lds_dwordx4 v164, s[26:27]
	s_add_i32 m0, s28, 0x2000
	s_nop 0
	global_load_lds_dwordx4 v168, s[26:27]
	s_mov_b32 m0, s36
	s_nop 0
	global_load_lds_dwordx4 v162, s[24:25]
	s_mov_b32 m0, s37
	s_nop 0
	global_load_lds_dwordx4 v166, s[24:25]
	s_waitcnt vmcnt(8)
	s_waitcnt lgkmcnt(0)
	s_setprio 1
	s_barrier
	v_mfma_f32_16x16x128_f8f6f4 v[94:97], v[2:9], v[184:191], v[94:97]
	v_mfma_f32_16x16x128_f8f6f4 v[90:93], v[10:17], v[184:191], v[90:93]
	v_mfma_f32_16x16x128_f8f6f4 v[78:81], v[2:9], v[192:199], v[78:81]
	v_mfma_f32_16x16x128_f8f6f4 v[74:77], v[10:17], v[192:199], v[74:77]
	v_mfma_f32_16x16x128_f8f6f4 v[62:65], v[2:9], v[220:227], v[62:65]
	v_mfma_f32_16x16x128_f8f6f4 v[58:61], v[10:17], v[220:227], v[58:61]
	v_mfma_f32_16x16x128_f8f6f4 v[46:49], v[2:9], v[228:235], v[46:49]
	v_mfma_f32_16x16x128_f8f6f4 v[42:45], v[10:17], v[228:235], v[42:45]
	s_setprio 0
	s_setprio 1
	v_mfma_f32_16x16x128_f8f6f4 v[86:89], v[18:25], v[184:191], v[86:89]
	v_mfma_f32_16x16x128_f8f6f4 v[82:85], v[26:33], v[184:191], v[82:85]
	v_mfma_f32_16x16x128_f8f6f4 v[70:73], v[18:25], v[192:199], v[70:73]
	v_mfma_f32_16x16x128_f8f6f4 v[66:69], v[26:33], v[192:199], v[66:69]
	v_mfma_f32_16x16x128_f8f6f4 v[54:57], v[18:25], v[220:227], v[54:57]
	v_mfma_f32_16x16x128_f8f6f4 v[50:53], v[26:33], v[220:227], v[50:53]
	v_mfma_f32_16x16x128_f8f6f4 v[38:41], v[18:25], v[228:235], v[38:41]
	v_mfma_f32_16x16x128_f8f6f4 v[34:37], v[26:33], v[228:235], v[34:37]
	s_barrier
	s_setprio 0
	s_add_i32 s44, s44, 2
	s_add_u32 s42, s42, 0x100000
	s_addc_u32 s43, s43, 0
	s_add_u32 s22, s22, 0x200000
	s_addc_u32 s23, s23, 0
	s_cmpk_gt_u32 s44, 0x6d
	s_cbranch_scc0 .LBB0_2714
	s_and_b64 vcc, exec, s[10:11]
	s_cbranch_vccz .LBB0_2717
	s_barrier
